# GLA: add the missing workgroup barrier before PART is rewritten for the next chunk (fixes a latent LDS race present in the baseline); plus pool ring-init parallel loads
# speedup vs baseline: 1.0173x; 1.0002x over previous
; #define LAS __attribute__((address_space(3)))
; #define LDS_BARRIER() asm volatile("s_waitcnt lgkmcnt(0)\n\ts_barrier" ::: "memory")
; __device__ __forceinline__ void gla_phase(LAS unsigned char* lds, const bf16_t* P, const float* hn, bf16_t* O, int G, int wg) {
;     ...
;         for (int c = 0; c < 32; ++c) {
;             float q0[8], q1[8], l0[8], l1[8], b0[8], b1[8]; unsigned vt0[4], vt1[4];
;             float run0 = 0.f, run1 = 0.f;
; #pragma unroll
;             for (int i = 0; i < 8; ++i) { q0[i] = bf2f(rq[i]); q1[i] = bf2f(rq[i] >> 16); l0[i] = bf2f(rl[i]) * LOG2E; l1[i] = bf2f(rl[i] >> 16) * LOG2E; run0 += l0[i]; b0[i] = run0; run1 += l1[i]; b1[i] = run1; }
; #pragma unroll
;             for (int i = 0; i < 4; ++i) { vt0[i] = (rv[2 * i] & 0xffffu) | (rv[2 * i + 1] << 16); vt1[i] = (rv[2 * i] >> 16) | (rv[2 * i + 1] & 0xffff0000u); }
;             { const int cn = (c < 31) ? c + 1 : 31;
;               const bf16_t* pp = pbase + (size_t)(cn * 64 + tq * 8) * 4096;
; #pragma unroll
;                 for (int i = 0; i < 8; ++i) { rq[i] = *(const unsigned*)(pp + (size_t)i * 4096); rl[i] = *(const unsigned*)(pp + (size_t)i * 4096 + 1024); rv[i] = *(const unsigned*)(pp + (size_t)i * 4096 + 2048); } }
;             *(LAS f32x2*)(lds + PART + (tq * 128 + 2 * dp) * 4) = (f32x2){run0, run1};
;             LDS_BARRIER();
.LBB0_1402:
	s_add_i32 s94, s95, 64
	s_cmpk_eq_i32 s95, 0x7c0
	s_cselect_b32 s16, s95, s94
	v_add_u32_e32 v16, s16, v82
	v_ashrrev_i32_e32 v17, 31, v16
	v_lshlrev_b64 v[16:17], 13, v[16:17]
	v_lshl_add_u64 v[16:17], v[102:103], 0, v[16:17]
	v_add_co_u32_e32 v18, vcc, s23, v16
	s_waitcnt vmcnt(20)
	v_lshlrev_b32_e32 v40, 16, v93
	v_addc_co_u32_e32 v19, vcc, 0, v17, vcc
	v_add_co_u32_e32 v20, vcc, s31, v16
	v_and_b32_e32 v41, 0xffff0000, v93
	s_nop 0
	v_addc_co_u32_e32 v21, vcc, 0, v17, vcc
	v_add_co_u32_e32 v22, vcc, s33, v16
	s_waitcnt vmcnt(17)
	v_lshlrev_b32_e32 v42, 16, v97
	v_addc_co_u32_e32 v23, vcc, 0, v17, vcc
	v_add_co_u32_e32 v24, vcc, s19, v16
	v_and_b32_e32 v43, 0xffff0000, v97
	s_nop 0
	v_addc_co_u32_e32 v25, vcc, 0, v17, vcc
	v_add_co_u32_e32 v26, vcc, s92, v16
	s_waitcnt vmcnt(14)
	v_lshlrev_b32_e32 v44, 16, v185
	v_addc_co_u32_e32 v27, vcc, 0, v17, vcc
	v_and_b32_e32 v45, 0xffff0000, v185
	global_load_dword v191, v[22:23], off
	global_load_dword v93, v[22:23], off offset:2048
	global_load_dword v194, v[24:25], off offset:-4096
	global_load_dword v192, v[24:25], off
	global_load_dword v97, v[24:25], off offset:2048
	global_load_dword v195, v[26:27], off offset:-4096
	global_load_dword v193, v[26:27], off
	global_load_dword v185, v[26:27], off offset:2048
	v_add_co_u32_e32 v24, vcc, 0xb000, v16
	s_waitcnt vmcnt(14)
	v_lshlrev_b32_e32 v34, 16, v189
	v_addc_co_u32_e32 v25, vcc, 0, v17, vcc
	v_add_co_u32_e32 v26, vcc, s12, v16
	v_and_b32_e32 v35, 0xffff0000, v189
	s_nop 0
	v_addc_co_u32_e32 v27, vcc, 0, v17, vcc
	v_add_co_u32_e32 v28, vcc, 0xd000, v16
	v_lshlrev_b32_e32 v46, 16, v187
	s_nop 0
	v_addc_co_u32_e32 v29, vcc, 0, v17, vcc
	v_add_co_u32_e32 v30, vcc, 0xe000, v16
	v_and_b32_e32 v47, 0xffff0000, v187
	s_nop 0
	v_addc_co_u32_e32 v31, vcc, 0, v17, vcc
	v_lshlrev_b32_e32 v48, 16, v188
	v_and_b32_e32 v49, 0xffff0000, v188
	global_load_dword v197, v[16:17], off
	global_load_dword v189, v[16:17], off offset:2048
	global_load_dword v199, v[24:25], off
	global_load_dword v196, v[26:27], off
	global_load_dword v187, v[26:27], off offset:2048
	global_load_dword v201, v[28:29], off
	global_load_dword v198, v[30:31], off
	global_load_dword v188, v[30:31], off offset:2048
	v_add_co_u32_e32 v16, vcc, 0xf000, v16
	s_waitcnt vmcnt(19)
	v_lshlrev_b32_e32 v36, 16, v190
	v_and_b32_e32 v37, 0xffff0000, v190
	v_lshlrev_b32_e32 v38, 16, v186
	v_and_b32_e32 v39, 0xffff0000, v186
	v_addc_co_u32_e32 v17, vcc, 0, v17, vcc
	global_load_dword v203, v[18:19], off offset:-4096
	global_load_dword v200, v[18:19], off
	global_load_dword v190, v[18:19], off offset:2048
	global_load_dword v204, v[20:21], off offset:-4096
	global_load_dword v202, v[20:21], off
	global_load_dword v186, v[20:21], off offset:2048
	global_load_dword v206, v[22:23], off offset:-4096
	global_load_dword v205, v[16:17], off
	v_pk_fma_f32 v[30:31], v[34:35], s[18:19], 0 op_sel_hi:[1,0,0]
	s_cmp_eq_u32 s95, 0
	v_pk_fma_f32 v[28:29], v[36:37], s[18:19], v[30:31] op_sel_hi:[1,0,1]
	s_mov_b32 s16, 0
	v_pk_fma_f32 v[26:27], v[38:39], s[18:19], v[28:29] op_sel_hi:[1,0,1]
	s_nop 0
	v_pk_fma_f32 v[24:25], v[40:41], s[18:19], v[26:27] op_sel_hi:[1,0,1]
	s_nop 0
	v_pk_fma_f32 v[22:23], v[42:43], s[18:19], v[24:25] op_sel_hi:[1,0,1]
	s_nop 0
	v_pk_fma_f32 v[20:21], v[44:45], s[18:19], v[22:23] op_sel_hi:[1,0,1]
	s_nop 0
	v_pk_fma_f32 v[18:19], v[46:47], s[18:19], v[20:21] op_sel_hi:[1,0,1]
	s_nop 0
	v_pk_fma_f32 v[16:17], v[48:49], s[18:19], v[18:19] op_sel_hi:[1,0,1]
	s_waitcnt lgkmcnt(0)
	s_barrier
	ds_write_b64 v161, v[16:17]
	s_waitcnt lgkmcnt(0)
	s_barrier
	s_cbranch_scc1 .LBB0_1404
	ds_read2st64_b32 v[50:51], v146 offset1:1
	s_sub_i32 s16, s95, 64
	s_waitcnt lgkmcnt(0)
	v_add_f32_e32 v32, v50, v51
	v_add_u32_e32 v50, 0, v147
	v_fmamk_f32 v32, v32, 0x3c000000, v211
	v_add_u32_e32 v56, 0x1b200, v50
	v_rsq_f32_e32 v32, v32
	ds_read_b128 v[50:53], v56
	v_pk_mul_f32 v[12:13], v[12:13], v[32:33] op_sel_hi:[1,0]
	v_pk_mul_f32 v[8:9], v[8:9], v[32:33] op_sel_hi:[1,0]
	s_waitcnt lgkmcnt(0)
	v_pk_mul_f32 v[12:13], v[50:51], v[12:13]
	v_lshlrev_b32_e32 v50, 16, v142
	v_and_b32_e32 v51, 0xffff0000, v142
	v_pk_mul_f32 v[12:13], v[12:13], v[50:51]
	v_pk_mul_f32 v[4:5], v[4:5], v[32:33] op_sel_hi:[1,0]
	v_cvt_pk_bf16_f32 v50, v12, v13
	v_pk_mul_f32 v[12:13], v[14:15], v[32:33] op_sel_hi:[1,0]
	v_lshlrev_b32_e32 v14, 16, v143
	v_pk_mul_f32 v[12:13], v[52:53], v[12:13]
	v_and_b32_e32 v15, 0xffff0000, v143
	v_pk_mul_f32 v[12:13], v[12:13], v[14:15]
	v_pk_mul_f32 v[0:1], v[0:1], v[32:33] op_sel_hi:[1,0]
	v_cvt_pk_bf16_f32 v51, v12, v13
	ds_read_b128 v[12:15], v56 offset:64
	s_waitcnt lgkmcnt(0)
	v_pk_mul_f32 v[8:9], v[12:13], v[8:9]
	s_waitcnt vmcnt(26)
	v_lshlrev_b32_e32 v12, 16, v140
	v_and_b32_e32 v13, 0xffff0000, v140
	v_pk_mul_f32 v[8:9], v[8:9], v[12:13]
	s_nop 0
	v_cvt_pk_bf16_f32 v12, v8, v9
	v_pk_mul_f32 v[8:9], v[10:11], v[32:33] op_sel_hi:[1,0]
	v_lshlrev_b32_e32 v10, 16, v141
	v_pk_mul_f32 v[8:9], v[14:15], v[8:9]
	v_and_b32_e32 v11, 0xffff0000, v141
	v_pk_mul_f32 v[8:9], v[8:9], v[10:11]
	s_nop 0
	v_cvt_pk_bf16_f32 v13, v8, v9
	ds_read_b128 v[8:11], v56 offset:128
	s_waitcnt lgkmcnt(0)
	v_pk_mul_f32 v[4:5], v[8:9], v[4:5]
	s_waitcnt vmcnt(25)
	v_lshlrev_b32_e32 v8, 16, v114
	v_and_b32_e32 v9, 0xffff0000, v114
	v_pk_mul_f32 v[4:5], v[4:5], v[8:9]
	s_nop 0
	v_cvt_pk_bf16_f32 v8, v4, v5
	v_pk_mul_f32 v[4:5], v[6:7], v[32:33] op_sel_hi:[1,0]
	v_lshlrev_b32_e32 v6, 16, v115
	v_pk_mul_f32 v[4:5], v[10:11], v[4:5]
	v_and_b32_e32 v7, 0xffff0000, v115
	v_pk_mul_f32 v[4:5], v[4:5], v[6:7]
	s_nop 0
	v_cvt_pk_bf16_f32 v9, v4, v5
	ds_read_b128 v[4:7], v56 offset:192
	s_waitcnt lgkmcnt(0)
	v_pk_mul_f32 v[0:1], v[0:1], v[4:5]
	s_waitcnt vmcnt(24)
	v_lshlrev_b32_e32 v4, 16, v100
	v_and_b32_e32 v5, 0xffff0000, v100
	v_pk_mul_f32 v[0:1], v[0:1], v[4:5]
	s_nop 0
	v_cvt_pk_bf16_f32 v10, v0, v1
	v_pk_mul_f32 v[0:1], v[2:3], v[32:33] op_sel_hi:[1,0]
	v_lshlrev_b32_e32 v2, 16, v101
	v_pk_mul_f32 v[0:1], v[0:1], v[6:7]
	v_and_b32_e32 v3, 0xffff0000, v101
	v_pk_mul_f32 v[0:1], v[0:1], v[2:3]
	v_and_b32_e32 v3, 64, v213
	v_xor_b32_e32 v2, 16, v213
	v_add_u32_e32 v3, 64, v3
	v_cmp_lt_i32_e32 vcc, v2, v3
	v_cvt_pk_bf16_f32 v6, v0, v1
	v_lshl_add_u64 v[0:1], v[98:99], 0, s[16:17]
	v_cndmask_b32_e32 v2, v213, v2, vcc
	v_lshlrev_b32_e32 v7, 2, v2
	v_lshlrev_b64 v[4:5], 11, v[0:1]
	v_cndmask_b32_e64 v0, v50, v12, s[42:43]
	v_cndmask_b32_e64 v1, v51, v13, s[42:43]
	ds_bpermute_b32 v0, v7, v0
	ds_bpermute_b32 v1, v7, v1
	v_lshl_add_u64 v[4:5], v[104:105], 0, v[4:5]
	s_mov_b32 s16, s95
	s_waitcnt lgkmcnt(1)
	v_cndmask_b32_e64 v2, v12, v0, s[42:43]
	s_waitcnt lgkmcnt(0)
	v_cndmask_b32_e64 v3, v13, v1, s[42:43]
	v_cndmask_b32_e64 v1, v1, v51, s[42:43]
	v_cndmask_b32_e64 v0, v0, v50, s[42:43]
	global_store_dwordx4 v[4:5], v[0:3], off
	s_nop 1
	v_cndmask_b32_e64 v0, v8, v10, s[42:43]
	v_cndmask_b32_e64 v1, v9, v6, s[42:43]
	ds_bpermute_b32 v0, v7, v0
	ds_bpermute_b32 v1, v7, v1
	s_waitcnt lgkmcnt(1)
	v_cndmask_b32_e64 v2, v10, v0, s[42:43]
	s_waitcnt lgkmcnt(0)
	v_cndmask_b32_e64 v3, v6, v1, s[42:43]
	v_cndmask_b32_e64 v1, v1, v9, s[42:43]
	v_cndmask_b32_e64 v0, v0, v8, s[42:43]
	global_store_dwordx4 v[4:5], v[0:3], off offset:64
